# MFMA snake order in GEMM K-loops: consecutive MFMAs share accumulator or one operand (on top of fast XCD barrier stack)
# speedup vs baseline: 1.0049x; 1.0049x over previous
.LBB0_566:
	s_add_u32 s30, s0, 0xfffc0080
	s_addc_u32 s31, s1, -1
	s_add_i32 s52, 0, 0x10000
	s_cmp_eq_u32 s51, 12
	s_cselect_b32 s35, s3, s31
	s_cselect_b32 s34, s25, s30
	s_cselect_b32 s31, s23, s50
	s_cselect_b32 s30, s48, s49
	s_add_i32 s54, 0, 0x14000
	v_add_u32_e32 v158, s52, v199
	v_add_u32_e32 v174, s54, v199
	ds_read_b128 v[134:137], v158
	ds_read_b128 v[150:153], v158 offset:1024
	ds_read_b128 v[154:157], v158 offset:2048
	ds_read_b128 v[158:161], v158 offset:3072
	ds_read_b128 v[162:165], v174
	ds_read_b128 v[166:169], v174 offset:1024
	ds_read_b128 v[170:173], v174 offset:2048
	ds_read_b128 v[182:185], v174 offset:3072
	v_lshl_add_u64 v[174:175], s[0:1], 0, v[146:147]
	s_add_i32 m0, s39, 0xc000
	ds_read_b128 v[186:189], v201
	ds_read_b128 v[202:205], v201 offset:1024
	ds_read_b128 v[206:209], v201 offset:2048
	ds_read_b128 v[210:213], v201 offset:3072
	ds_read_b128 v[214:217], v201 offset:4096
	ds_read_b128 v[218:221], v201 offset:5120
	ds_read_b128 v[222:225], v201 offset:6144
	ds_read_b128 v[226:229], v201 offset:7168
	global_load_lds_dwordx4 v[174:175], off
	v_lshl_add_u64 v[174:175], s[0:1], 0, v[148:149]
	s_add_i32 m0, s39, 0xe000
	s_nop 0
	global_load_lds_dwordx4 v[174:175], off
	s_waitcnt vmcnt(8)
	s_waitcnt lgkmcnt(0)
	s_barrier
	s_setprio 1
	s_waitcnt lgkmcnt(0)
	v_mfma_f32_16x16x32_bf16 v[130:133], v[134:137], v[186:189], v[130:133]
	v_mfma_f32_16x16x32_bf16 v[130:133], v[150:153], v[202:205], v[130:133]
	v_mfma_f32_16x16x32_bf16 v[126:129], v[158:161], v[202:205], v[126:129]
	v_mfma_f32_16x16x32_bf16 v[126:129], v[154:157], v[186:189], v[126:129]
	v_mfma_f32_16x16x32_bf16 v[110:113], v[154:157], v[206:209], v[110:113]
	v_mfma_f32_16x16x32_bf16 v[110:113], v[158:161], v[210:213], v[110:113]
	v_mfma_f32_16x16x32_bf16 v[114:117], v[150:153], v[210:213], v[114:117]
	v_mfma_f32_16x16x32_bf16 v[114:117], v[134:137], v[206:209], v[114:117]
	v_mfma_f32_16x16x32_bf16 v[98:101], v[134:137], v[214:217], v[98:101]
	v_mfma_f32_16x16x32_bf16 v[98:101], v[150:153], v[218:221], v[98:101]
	v_mfma_f32_16x16x32_bf16 v[94:97], v[158:161], v[218:221], v[94:97]
	v_mfma_f32_16x16x32_bf16 v[94:97], v[154:157], v[214:217], v[94:97]
	v_mfma_f32_16x16x32_bf16 v[78:81], v[154:157], v[222:225], v[78:81]
	v_mfma_f32_16x16x32_bf16 v[78:81], v[158:161], v[226:229], v[78:81]
	v_mfma_f32_16x16x32_bf16 v[82:85], v[150:153], v[226:229], v[82:85]
	v_mfma_f32_16x16x32_bf16 v[82:85], v[134:137], v[222:225], v[82:85]
	s_setprio 0
	s_setprio 1
	v_mfma_f32_16x16x32_bf16 v[122:125], v[162:165], v[186:189], v[122:125]
	v_mfma_f32_16x16x32_bf16 v[122:125], v[166:169], v[202:205], v[122:125]
	v_mfma_f32_16x16x32_bf16 v[118:121], v[182:185], v[202:205], v[118:121]
	v_mfma_f32_16x16x32_bf16 v[118:121], v[170:173], v[186:189], v[118:121]
	v_mfma_f32_16x16x32_bf16 v[102:105], v[170:173], v[206:209], v[102:105]
	v_mfma_f32_16x16x32_bf16 v[102:105], v[182:185], v[210:213], v[102:105]
	v_mfma_f32_16x16x32_bf16 v[106:109], v[166:169], v[210:213], v[106:109]
	v_mfma_f32_16x16x32_bf16 v[106:109], v[162:165], v[206:209], v[106:109]
	v_mfma_f32_16x16x32_bf16 v[90:93], v[162:165], v[214:217], v[90:93]
	v_mfma_f32_16x16x32_bf16 v[90:93], v[166:169], v[218:221], v[90:93]
	v_mfma_f32_16x16x32_bf16 v[86:89], v[182:185], v[218:221], v[86:89]
	v_mfma_f32_16x16x32_bf16 v[86:89], v[170:173], v[214:217], v[86:89]
	v_mfma_f32_16x16x32_bf16 v[70:73], v[170:173], v[222:225], v[70:73]
	v_mfma_f32_16x16x32_bf16 v[70:73], v[182:185], v[226:229], v[70:73]
	v_mfma_f32_16x16x32_bf16 v[74:77], v[166:169], v[226:229], v[74:77]
	v_mfma_f32_16x16x32_bf16 v[74:77], v[162:165], v[222:225], v[74:77]
	s_setprio 0
	s_barrier
	s_add_i32 s52, s52, s36
	v_lshl_add_u64 v[174:175], s[30:31], 0, v[0:1]
	s_mov_b32 m0, s52
	ds_read_b128 v[186:189], v201 offset:16384
	ds_read_b128 v[202:205], v201 offset:17408
	ds_read_b128 v[206:209], v201 offset:18432
	ds_read_b128 v[210:213], v201 offset:19456
	ds_read_b128 v[214:217], v201 offset:20480
	ds_read_b128 v[218:221], v201 offset:21504
	ds_read_b128 v[222:225], v201 offset:22528
	ds_read_b128 v[226:229], v201 offset:23552
	global_load_lds_dwordx4 v[174:175], off
	s_add_i32 m0, s52, 0x2000
	s_add_u32 s52, s30, 0x40000
	v_lshl_add_u64 v[190:191], s[30:31], 0, v[14:15]
	s_addc_u32 s53, s31, 0
	s_add_i32 s54, s54, s36
	global_load_lds_dwordx4 v[190:191], off
	v_lshl_add_u64 v[230:231], s[52:53], 0, v[0:1]
	s_mov_b32 m0, s54
	v_lshl_add_u64 v[232:233], s[34:35], 0, v[138:139]
	global_load_lds_dwordx4 v[230:231], off
	v_lshl_add_u64 v[230:231], s[52:53], 0, v[14:15]
	s_add_i32 m0, s54, 0x2000
	s_nop 0
	global_load_lds_dwordx4 v[230:231], off
	v_lshl_add_u64 v[230:231], s[34:35], 0, v[140:141]
	s_mov_b32 m0, s39
	s_nop 0
	global_load_lds_dwordx4 v[230:231], off
	s_mov_b32 m0, s40
	s_nop 0
	global_load_lds_dwordx4 v[232:233], off
	s_waitcnt vmcnt(8)
	s_waitcnt lgkmcnt(0)
	s_barrier
	s_setprio 1
	s_waitcnt lgkmcnt(0)
	v_mfma_f32_16x16x32_bf16 v[66:69], v[134:137], v[186:189], v[66:69]
	v_mfma_f32_16x16x32_bf16 v[66:69], v[150:153], v[202:205], v[66:69]
	v_mfma_f32_16x16x32_bf16 v[62:65], v[158:161], v[202:205], v[62:65]
	v_mfma_f32_16x16x32_bf16 v[62:65], v[154:157], v[186:189], v[62:65]
	v_mfma_f32_16x16x32_bf16 v[46:49], v[154:157], v[206:209], v[46:49]
	v_mfma_f32_16x16x32_bf16 v[46:49], v[158:161], v[210:213], v[46:49]
	v_mfma_f32_16x16x32_bf16 v[50:53], v[150:153], v[210:213], v[50:53]
	v_mfma_f32_16x16x32_bf16 v[50:53], v[134:137], v[206:209], v[50:53]
	v_mfma_f32_16x16x32_bf16 v[34:37], v[134:137], v[214:217], v[34:37]
	v_mfma_f32_16x16x32_bf16 v[34:37], v[150:153], v[218:221], v[34:37]
	v_mfma_f32_16x16x32_bf16 v[30:33], v[158:161], v[218:221], v[30:33]
	v_mfma_f32_16x16x32_bf16 v[30:33], v[154:157], v[214:217], v[30:33]
	v_mfma_f32_16x16x32_bf16 v[10:13], v[154:157], v[222:225], v[10:13]
	v_mfma_f32_16x16x32_bf16 v[10:13], v[158:161], v[226:229], v[10:13]
	v_mfma_f32_16x16x32_bf16 v[18:21], v[150:153], v[226:229], v[18:21]
	v_mfma_f32_16x16x32_bf16 v[18:21], v[134:137], v[222:225], v[18:21]
	s_setprio 0
	s_setprio 1
	v_mfma_f32_16x16x32_bf16 v[58:61], v[162:165], v[186:189], v[58:61]
	v_mfma_f32_16x16x32_bf16 v[58:61], v[166:169], v[202:205], v[58:61]
	v_mfma_f32_16x16x32_bf16 v[54:57], v[182:185], v[202:205], v[54:57]
	v_mfma_f32_16x16x32_bf16 v[54:57], v[170:173], v[186:189], v[54:57]
	v_mfma_f32_16x16x32_bf16 v[38:41], v[170:173], v[206:209], v[38:41]
	v_mfma_f32_16x16x32_bf16 v[38:41], v[182:185], v[210:213], v[38:41]
	v_mfma_f32_16x16x32_bf16 v[42:45], v[166:169], v[210:213], v[42:45]
	v_mfma_f32_16x16x32_bf16 v[42:45], v[162:165], v[206:209], v[42:45]
	v_mfma_f32_16x16x32_bf16 v[26:29], v[162:165], v[214:217], v[26:29]
	v_mfma_f32_16x16x32_bf16 v[26:29], v[166:169], v[218:221], v[26:29]
	v_mfma_f32_16x16x32_bf16 v[22:25], v[182:185], v[218:221], v[22:25]
	v_mfma_f32_16x16x32_bf16 v[22:25], v[170:173], v[214:217], v[22:25]
	v_mfma_f32_16x16x32_bf16 v[2:5], v[170:173], v[222:225], v[2:5]
	v_mfma_f32_16x16x32_bf16 v[2:5], v[182:185], v[226:229], v[2:5]
	v_mfma_f32_16x16x32_bf16 v[6:9], v[166:169], v[226:229], v[6:9]
	v_mfma_f32_16x16x32_bf16 v[6:9], v[162:165], v[222:225], v[6:9]
	s_setprio 0
	s_barrier
	s_add_i32 s52, 0, 0x18000
	s_add_i32 s53, 0, 0x1c000
	v_add_u32_e32 v158, s52, v199
	v_add_u32_e32 v182, s53, v199
	ds_read_b128 v[134:137], v158
	ds_read_b128 v[150:153], v158 offset:1024
	ds_read_b128 v[154:157], v158 offset:2048
	ds_read_b128 v[158:161], v158 offset:3072
	ds_read_b128 v[162:165], v182
	ds_read_b128 v[166:169], v182 offset:1024
	ds_read_b128 v[170:173], v182 offset:2048
	ds_read_b128 v[182:185], v182 offset:3072
	s_add_u32 s34, s34, 0x40000
	s_addc_u32 s35, s35, 0
	s_mov_b32 m0, s41
	v_lshl_add_u64 v[234:235], s[34:35], 0, v[140:141]
	ds_read_b128 v[186:189], v201 offset:32768
	ds_read_b128 v[202:205], v201 offset:33792
	ds_read_b128 v[206:209], v201 offset:34816
	ds_read_b128 v[210:213], v201 offset:35840
	ds_read_b128 v[214:217], v201 offset:36864
	ds_read_b128 v[218:221], v201 offset:37888
	ds_read_b128 v[222:225], v201 offset:38912
	ds_read_b128 v[226:229], v201 offset:39936
	global_load_lds_dwordx4 v[234:235], off
	v_lshl_add_u64 v[234:235], s[34:35], 0, v[138:139]
	s_mov_b32 m0, s42
	s_nop 0
	global_load_lds_dwordx4 v[234:235], off
	s_waitcnt vmcnt(8)
	s_waitcnt lgkmcnt(0)
	s_barrier
	s_setprio 1
	s_waitcnt lgkmcnt(0)
	v_mfma_f32_16x16x32_bf16 v[130:133], v[134:137], v[186:189], v[130:133]
	v_mfma_f32_16x16x32_bf16 v[130:133], v[150:153], v[202:205], v[130:133]
	v_mfma_f32_16x16x32_bf16 v[126:129], v[158:161], v[202:205], v[126:129]
	v_mfma_f32_16x16x32_bf16 v[126:129], v[154:157], v[186:189], v[126:129]
	v_mfma_f32_16x16x32_bf16 v[110:113], v[154:157], v[206:209], v[110:113]
	v_mfma_f32_16x16x32_bf16 v[110:113], v[158:161], v[210:213], v[110:113]
	v_mfma_f32_16x16x32_bf16 v[114:117], v[150:153], v[210:213], v[114:117]
	v_mfma_f32_16x16x32_bf16 v[114:117], v[134:137], v[206:209], v[114:117]
	v_mfma_f32_16x16x32_bf16 v[98:101], v[134:137], v[214:217], v[98:101]
	v_mfma_f32_16x16x32_bf16 v[98:101], v[150:153], v[218:221], v[98:101]
	v_mfma_f32_16x16x32_bf16 v[94:97], v[158:161], v[218:221], v[94:97]
	v_mfma_f32_16x16x32_bf16 v[94:97], v[154:157], v[214:217], v[94:97]
	v_mfma_f32_16x16x32_bf16 v[78:81], v[154:157], v[222:225], v[78:81]
	v_mfma_f32_16x16x32_bf16 v[78:81], v[158:161], v[226:229], v[78:81]
	v_mfma_f32_16x16x32_bf16 v[82:85], v[150:153], v[226:229], v[82:85]
	v_mfma_f32_16x16x32_bf16 v[82:85], v[134:137], v[222:225], v[82:85]
	s_setprio 0
	s_setprio 1
	v_mfma_f32_16x16x32_bf16 v[122:125], v[162:165], v[186:189], v[122:125]
	v_mfma_f32_16x16x32_bf16 v[122:125], v[166:169], v[202:205], v[122:125]
	v_mfma_f32_16x16x32_bf16 v[118:121], v[182:185], v[202:205], v[118:121]
	v_mfma_f32_16x16x32_bf16 v[118:121], v[170:173], v[186:189], v[118:121]
	v_mfma_f32_16x16x32_bf16 v[102:105], v[170:173], v[206:209], v[102:105]
	v_mfma_f32_16x16x32_bf16 v[102:105], v[182:185], v[210:213], v[102:105]
	v_mfma_f32_16x16x32_bf16 v[106:109], v[166:169], v[210:213], v[106:109]
	v_mfma_f32_16x16x32_bf16 v[106:109], v[162:165], v[206:209], v[106:109]
	v_mfma_f32_16x16x32_bf16 v[90:93], v[162:165], v[214:217], v[90:93]
	v_mfma_f32_16x16x32_bf16 v[90:93], v[166:169], v[218:221], v[90:93]
	v_mfma_f32_16x16x32_bf16 v[86:89], v[182:185], v[218:221], v[86:89]
	v_mfma_f32_16x16x32_bf16 v[86:89], v[170:173], v[214:217], v[86:89]
	v_mfma_f32_16x16x32_bf16 v[70:73], v[170:173], v[222:225], v[70:73]
	v_mfma_f32_16x16x32_bf16 v[70:73], v[182:185], v[226:229], v[70:73]
	v_mfma_f32_16x16x32_bf16 v[74:77], v[166:169], v[226:229], v[74:77]
	v_mfma_f32_16x16x32_bf16 v[74:77], v[162:165], v[222:225], v[74:77]
	s_setprio 0
	s_barrier
	s_add_i32 s34, s52, s36
	v_lshl_add_u64 v[174:175], v[174:175], 0, s[92:93]
	s_mov_b32 m0, s34
	ds_read_b128 v[186:189], v201 offset:49152
	ds_read_b128 v[202:205], v201 offset:50176
	ds_read_b128 v[206:209], v201 offset:51200
	ds_read_b128 v[210:213], v201 offset:52224
	ds_read_b128 v[214:217], v201 offset:53248
	ds_read_b128 v[218:221], v201 offset:54272
	ds_read_b128 v[222:225], v201 offset:55296
	ds_read_b128 v[226:229], v201 offset:56320
	global_load_lds_dwordx4 v[174:175], off
	s_add_i32 m0, s34, 0x2000
	s_add_u32 s30, s30, 0x40080
	v_lshl_add_u64 v[174:175], v[190:191], 0, s[92:93]
	s_addc_u32 s31, s31, 0
	s_add_i32 s34, s53, s36
	global_load_lds_dwordx4 v[174:175], off
	v_lshl_add_u64 v[174:175], s[30:31], 0, v[0:1]
	s_mov_b32 m0, s34
	s_nop 0
	global_load_lds_dwordx4 v[174:175], off
	v_lshl_add_u64 v[174:175], s[30:31], 0, v[14:15]
	s_add_i32 m0, s34, 0x2000
	s_nop 0
	global_load_lds_dwordx4 v[174:175], off
	v_lshl_add_u64 v[174:175], v[230:231], 0, s[92:93]
	s_mov_b32 m0, s43
	s_nop 0
	global_load_lds_dwordx4 v[174:175], off
	v_lshl_add_u64 v[174:175], v[232:233], 0, s[92:93]
	s_mov_b32 m0, s44
	s_nop 0
	global_load_lds_dwordx4 v[174:175], off
	s_waitcnt vmcnt(8)
	s_waitcnt lgkmcnt(0)
	s_barrier
	s_setprio 1
	s_waitcnt lgkmcnt(0)
	v_mfma_f32_16x16x32_bf16 v[66:69], v[134:137], v[186:189], v[66:69]
	v_mfma_f32_16x16x32_bf16 v[66:69], v[150:153], v[202:205], v[66:69]
	v_mfma_f32_16x16x32_bf16 v[62:65], v[158:161], v[202:205], v[62:65]
	v_mfma_f32_16x16x32_bf16 v[62:65], v[154:157], v[186:189], v[62:65]
	v_mfma_f32_16x16x32_bf16 v[46:49], v[154:157], v[206:209], v[46:49]
	v_mfma_f32_16x16x32_bf16 v[46:49], v[158:161], v[210:213], v[46:49]
	v_mfma_f32_16x16x32_bf16 v[50:53], v[150:153], v[210:213], v[50:53]
	v_mfma_f32_16x16x32_bf16 v[50:53], v[134:137], v[206:209], v[50:53]
	v_mfma_f32_16x16x32_bf16 v[34:37], v[134:137], v[214:217], v[34:37]
	v_mfma_f32_16x16x32_bf16 v[34:37], v[150:153], v[218:221], v[34:37]
	v_mfma_f32_16x16x32_bf16 v[30:33], v[158:161], v[218:221], v[30:33]
	v_mfma_f32_16x16x32_bf16 v[30:33], v[154:157], v[214:217], v[30:33]
	v_mfma_f32_16x16x32_bf16 v[10:13], v[154:157], v[222:225], v[10:13]
	v_mfma_f32_16x16x32_bf16 v[10:13], v[158:161], v[226:229], v[10:13]
	v_mfma_f32_16x16x32_bf16 v[18:21], v[150:153], v[226:229], v[18:21]
	v_mfma_f32_16x16x32_bf16 v[18:21], v[134:137], v[222:225], v[18:21]
	s_setprio 0
	s_setprio 1
	v_mfma_f32_16x16x32_bf16 v[58:61], v[162:165], v[186:189], v[58:61]
	v_mfma_f32_16x16x32_bf16 v[58:61], v[166:169], v[202:205], v[58:61]
	v_mfma_f32_16x16x32_bf16 v[54:57], v[182:185], v[202:205], v[54:57]
	v_mfma_f32_16x16x32_bf16 v[54:57], v[170:173], v[186:189], v[54:57]
	v_mfma_f32_16x16x32_bf16 v[38:41], v[170:173], v[206:209], v[38:41]
	v_mfma_f32_16x16x32_bf16 v[38:41], v[182:185], v[210:213], v[38:41]
	v_mfma_f32_16x16x32_bf16 v[42:45], v[166:169], v[210:213], v[42:45]
	v_mfma_f32_16x16x32_bf16 v[42:45], v[162:165], v[206:209], v[42:45]
	v_mfma_f32_16x16x32_bf16 v[26:29], v[162:165], v[214:217], v[26:29]
	v_mfma_f32_16x16x32_bf16 v[26:29], v[166:169], v[218:221], v[26:29]
	v_mfma_f32_16x16x32_bf16 v[22:25], v[182:185], v[218:221], v[22:25]
	v_mfma_f32_16x16x32_bf16 v[22:25], v[170:173], v[214:217], v[22:25]
	v_mfma_f32_16x16x32_bf16 v[2:5], v[170:173], v[222:225], v[2:5]
	v_mfma_f32_16x16x32_bf16 v[2:5], v[182:185], v[226:229], v[2:5]
	v_mfma_f32_16x16x32_bf16 v[6:9], v[166:169], v[226:229], v[6:9]
	v_mfma_f32_16x16x32_bf16 v[6:9], v[162:165], v[222:225], v[6:9]
	s_setprio 0
	s_barrier
	s_add_i32 s51, s51, 2
	s_add_u32 s0, s0, 0x100
	s_addc_u32 s1, s1, 0
	s_add_u32 s49, s49, 0x100
	s_addc_u32 s50, s50, 0
	s_cmp_gt_u32 s51, 13
	s_cbranch_scc0 .LBB0_566
	s_and_b64 vcc, exec, s[18:19]
	s_cbranch_vccz .LBB0_569
	s_barrier

.LBB0_637:
	s_add_i32 s47, s24, 2
	s_add_u32 s48, s22, 0x80
	s_addc_u32 s25, s23, 0
	s_add_i32 s50, 0, 0x10000
	s_cmp_eq_u32 s40, s24
	s_cselect_b32 s25, s7, s25
	s_cselect_b32 s24, s6, s48
	v_add_u32_e32 v135, s50, v249
	s_cselect_b32 s49, s21, s46
	s_cselect_b32 s48, s20, s45
	s_add_i32 s51, 0, 0x14000
	ds_read_b128 v[142:145], v135
	ds_read_b128 v[146:149], v135 offset:1024
	ds_read_b128 v[150:153], v135 offset:2048
	ds_read_b128 v[154:157], v135 offset:3072
	v_add_u32_e32 v135, s51, v249
	ds_read_b128 v[158:161], v135
	ds_read_b128 v[162:165], v135 offset:1024
	ds_read_b128 v[166:169], v135 offset:2048
	ds_read_b128 v[170:173], v135 offset:3072
	v_lshl_add_u64 v[174:175], s[22:23], 0, v[138:139]
	s_add_i32 m0, s31, 0xc000
	ds_read_b128 v[182:185], v251
	ds_read_b128 v[186:189], v251 offset:1024
	ds_read_b128 v[190:193], v251 offset:2048
	ds_read_b128 v[194:197], v251 offset:3072
	ds_read_b128 v[198:201], v251 offset:4096
	ds_read_b128 v[202:205], v251 offset:5120
	ds_read_b128 v[206:209], v251 offset:6144
	ds_read_b128 v[210:213], v251 offset:7168
	global_load_lds_dwordx4 v[174:175], off
	v_lshl_add_u64 v[174:175], s[22:23], 0, v[140:141]
	s_add_i32 m0, s31, 0xe000
	s_nop 0
	global_load_lds_dwordx4 v[174:175], off
	s_waitcnt vmcnt(8)
	s_waitcnt lgkmcnt(0)
	s_barrier
	s_setprio 1
	s_waitcnt lgkmcnt(0)
	v_mfma_f32_16x16x32_bf16 v[130:133], v[142:145], v[182:185], v[130:133]
	v_mfma_f32_16x16x32_bf16 v[130:133], v[146:149], v[186:189], v[130:133]
	v_mfma_f32_16x16x32_bf16 v[126:129], v[154:157], v[186:189], v[126:129]
	v_mfma_f32_16x16x32_bf16 v[126:129], v[150:153], v[182:185], v[126:129]
	v_mfma_f32_16x16x32_bf16 v[110:113], v[150:153], v[190:193], v[110:113]
	v_mfma_f32_16x16x32_bf16 v[110:113], v[154:157], v[194:197], v[110:113]
	v_mfma_f32_16x16x32_bf16 v[114:117], v[146:149], v[194:197], v[114:117]
	v_mfma_f32_16x16x32_bf16 v[114:117], v[142:145], v[190:193], v[114:117]
	v_mfma_f32_16x16x32_bf16 v[98:101], v[142:145], v[198:201], v[98:101]
	v_mfma_f32_16x16x32_bf16 v[98:101], v[146:149], v[202:205], v[98:101]
	v_mfma_f32_16x16x32_bf16 v[94:97], v[154:157], v[202:205], v[94:97]
	v_mfma_f32_16x16x32_bf16 v[94:97], v[150:153], v[198:201], v[94:97]
	v_mfma_f32_16x16x32_bf16 v[78:81], v[150:153], v[206:209], v[78:81]
	v_mfma_f32_16x16x32_bf16 v[78:81], v[154:157], v[210:213], v[78:81]
	v_mfma_f32_16x16x32_bf16 v[82:85], v[146:149], v[210:213], v[82:85]
	v_mfma_f32_16x16x32_bf16 v[82:85], v[142:145], v[206:209], v[82:85]
	s_setprio 0
	s_setprio 1
	v_mfma_f32_16x16x32_bf16 v[122:125], v[158:161], v[182:185], v[122:125]
	v_mfma_f32_16x16x32_bf16 v[122:125], v[162:165], v[186:189], v[122:125]
	v_mfma_f32_16x16x32_bf16 v[118:121], v[170:173], v[186:189], v[118:121]
	v_mfma_f32_16x16x32_bf16 v[118:121], v[166:169], v[182:185], v[118:121]
	v_mfma_f32_16x16x32_bf16 v[102:105], v[166:169], v[190:193], v[102:105]
	v_mfma_f32_16x16x32_bf16 v[102:105], v[170:173], v[194:197], v[102:105]
	v_mfma_f32_16x16x32_bf16 v[106:109], v[162:165], v[194:197], v[106:109]
	v_mfma_f32_16x16x32_bf16 v[106:109], v[158:161], v[190:193], v[106:109]
	v_mfma_f32_16x16x32_bf16 v[90:93], v[158:161], v[198:201], v[90:93]
	v_mfma_f32_16x16x32_bf16 v[90:93], v[162:165], v[202:205], v[90:93]
	v_mfma_f32_16x16x32_bf16 v[86:89], v[170:173], v[202:205], v[86:89]
	v_mfma_f32_16x16x32_bf16 v[86:89], v[166:169], v[198:201], v[86:89]
	v_mfma_f32_16x16x32_bf16 v[70:73], v[166:169], v[206:209], v[70:73]
	v_mfma_f32_16x16x32_bf16 v[70:73], v[170:173], v[210:213], v[70:73]
	v_mfma_f32_16x16x32_bf16 v[74:77], v[162:165], v[210:213], v[74:77]
	v_mfma_f32_16x16x32_bf16 v[74:77], v[158:161], v[206:209], v[74:77]
	s_setprio 0
	s_barrier
	s_add_i32 s50, s50, s30
	v_lshl_add_u64 v[174:175], s[48:49], 0, v[0:1]
	s_mov_b32 m0, s50
	ds_read_b128 v[182:185], v251 offset:16384
	ds_read_b128 v[186:189], v251 offset:17408
	ds_read_b128 v[190:193], v251 offset:18432
	ds_read_b128 v[194:197], v251 offset:19456
	ds_read_b128 v[198:201], v251 offset:20480
	ds_read_b128 v[202:205], v251 offset:21504
	ds_read_b128 v[206:209], v251 offset:22528
	ds_read_b128 v[210:213], v251 offset:23552
	global_load_lds_dwordx4 v[174:175], off
	s_add_i32 m0, s50, 0x2000
	v_lshl_add_u64 v[214:215], s[48:49], 0, v[14:15]
	s_add_u32 s48, s48, s10
	s_addc_u32 s49, s49, 0
	s_add_i32 s50, s51, s30
	global_load_lds_dwordx4 v[214:215], off
	v_lshl_add_u64 v[216:217], s[48:49], 0, v[0:1]
	s_mov_b32 m0, s50
	v_lshl_add_u64 v[218:219], s[48:49], 0, v[14:15]
	global_load_lds_dwordx4 v[216:217], off
	s_add_i32 m0, s50, 0x2000
	v_lshl_add_u64 v[220:221], s[24:25], 0, v[0:1]
	global_load_lds_dwordx4 v[218:219], off
	s_mov_b32 m0, s31
	v_lshl_add_u64 v[222:223], s[24:25], 0, v[14:15]
	global_load_lds_dwordx4 v[220:221], off
	s_mov_b32 m0, s34
	s_nop 0
	global_load_lds_dwordx4 v[222:223], off
	s_waitcnt vmcnt(8)
	s_waitcnt lgkmcnt(0)
	s_barrier
	s_setprio 1
	s_waitcnt lgkmcnt(0)
	v_mfma_f32_16x16x32_bf16 v[66:69], v[142:145], v[182:185], v[66:69]
	v_mfma_f32_16x16x32_bf16 v[66:69], v[146:149], v[186:189], v[66:69]
	v_mfma_f32_16x16x32_bf16 v[62:65], v[154:157], v[186:189], v[62:65]
	v_mfma_f32_16x16x32_bf16 v[62:65], v[150:153], v[182:185], v[62:65]
	v_mfma_f32_16x16x32_bf16 v[46:49], v[150:153], v[190:193], v[46:49]
	v_mfma_f32_16x16x32_bf16 v[46:49], v[154:157], v[194:197], v[46:49]
	v_mfma_f32_16x16x32_bf16 v[50:53], v[146:149], v[194:197], v[50:53]
	v_mfma_f32_16x16x32_bf16 v[50:53], v[142:145], v[190:193], v[50:53]
	v_mfma_f32_16x16x32_bf16 v[34:37], v[142:145], v[198:201], v[34:37]
	v_mfma_f32_16x16x32_bf16 v[34:37], v[146:149], v[202:205], v[34:37]
	v_mfma_f32_16x16x32_bf16 v[30:33], v[154:157], v[202:205], v[30:33]
	v_mfma_f32_16x16x32_bf16 v[30:33], v[150:153], v[198:201], v[30:33]
	v_mfma_f32_16x16x32_bf16 v[10:13], v[150:153], v[206:209], v[10:13]
	v_mfma_f32_16x16x32_bf16 v[10:13], v[154:157], v[210:213], v[10:13]
	v_mfma_f32_16x16x32_bf16 v[18:21], v[146:149], v[210:213], v[18:21]
	v_mfma_f32_16x16x32_bf16 v[18:21], v[142:145], v[206:209], v[18:21]
	s_setprio 0
	s_setprio 1
	v_mfma_f32_16x16x32_bf16 v[58:61], v[158:161], v[182:185], v[58:61]
	v_mfma_f32_16x16x32_bf16 v[58:61], v[162:165], v[186:189], v[58:61]
	v_mfma_f32_16x16x32_bf16 v[54:57], v[170:173], v[186:189], v[54:57]
	v_mfma_f32_16x16x32_bf16 v[54:57], v[166:169], v[182:185], v[54:57]
	v_mfma_f32_16x16x32_bf16 v[38:41], v[166:169], v[190:193], v[38:41]
	v_mfma_f32_16x16x32_bf16 v[38:41], v[170:173], v[194:197], v[38:41]
	v_mfma_f32_16x16x32_bf16 v[42:45], v[162:165], v[194:197], v[42:45]
	v_mfma_f32_16x16x32_bf16 v[42:45], v[158:161], v[190:193], v[42:45]
	v_mfma_f32_16x16x32_bf16 v[26:29], v[158:161], v[198:201], v[26:29]
	v_mfma_f32_16x16x32_bf16 v[26:29], v[162:165], v[202:205], v[26:29]
	v_mfma_f32_16x16x32_bf16 v[22:25], v[170:173], v[202:205], v[22:25]
	v_mfma_f32_16x16x32_bf16 v[22:25], v[166:169], v[198:201], v[22:25]
	v_mfma_f32_16x16x32_bf16 v[2:5], v[166:169], v[206:209], v[2:5]
	v_mfma_f32_16x16x32_bf16 v[2:5], v[170:173], v[210:213], v[2:5]
	v_mfma_f32_16x16x32_bf16 v[6:9], v[162:165], v[210:213], v[6:9]
	v_mfma_f32_16x16x32_bf16 v[6:9], v[158:161], v[206:209], v[6:9]
	s_setprio 0
	s_barrier
	s_add_i32 s48, 0, 0x18000
	v_add_u32_e32 v135, s48, v249
	s_add_i32 s49, 0, 0x1c000
	ds_read_b128 v[142:145], v135
	ds_read_b128 v[146:149], v135 offset:1024
	ds_read_b128 v[150:153], v135 offset:2048
	ds_read_b128 v[154:157], v135 offset:3072
	v_add_u32_e32 v135, s49, v249
	ds_read_b128 v[158:161], v135
	ds_read_b128 v[162:165], v135 offset:1024
	ds_read_b128 v[166:169], v135 offset:2048
	ds_read_b128 v[170:173], v135 offset:3072
	s_add_u32 s24, s24, s10
	s_addc_u32 s25, s25, 0
	s_mov_b32 m0, s35
	v_lshl_add_u64 v[224:225], s[24:25], 0, v[0:1]
	ds_read_b128 v[182:185], v251 offset:32768
	ds_read_b128 v[186:189], v251 offset:33792
	ds_read_b128 v[190:193], v251 offset:34816
	ds_read_b128 v[194:197], v251 offset:35840
	ds_read_b128 v[198:201], v251 offset:36864
	ds_read_b128 v[202:205], v251 offset:37888
	ds_read_b128 v[206:209], v251 offset:38912
	ds_read_b128 v[210:213], v251 offset:39936
	global_load_lds_dwordx4 v[224:225], off
	v_lshl_add_u64 v[224:225], s[24:25], 0, v[14:15]
	s_mov_b32 m0, s36
	s_nop 0
	global_load_lds_dwordx4 v[224:225], off
	s_waitcnt vmcnt(8)
	s_waitcnt lgkmcnt(0)
	s_barrier
	s_setprio 1
	s_waitcnt lgkmcnt(0)
	v_mfma_f32_16x16x32_bf16 v[130:133], v[142:145], v[182:185], v[130:133]
	v_mfma_f32_16x16x32_bf16 v[130:133], v[146:149], v[186:189], v[130:133]
	v_mfma_f32_16x16x32_bf16 v[126:129], v[154:157], v[186:189], v[126:129]
	v_mfma_f32_16x16x32_bf16 v[126:129], v[150:153], v[182:185], v[126:129]
	v_mfma_f32_16x16x32_bf16 v[110:113], v[150:153], v[190:193], v[110:113]
	v_mfma_f32_16x16x32_bf16 v[110:113], v[154:157], v[194:197], v[110:113]
	v_mfma_f32_16x16x32_bf16 v[114:117], v[146:149], v[194:197], v[114:117]
	v_mfma_f32_16x16x32_bf16 v[114:117], v[142:145], v[190:193], v[114:117]
	v_mfma_f32_16x16x32_bf16 v[98:101], v[142:145], v[198:201], v[98:101]
	v_mfma_f32_16x16x32_bf16 v[98:101], v[146:149], v[202:205], v[98:101]
	v_mfma_f32_16x16x32_bf16 v[94:97], v[154:157], v[202:205], v[94:97]
	v_mfma_f32_16x16x32_bf16 v[94:97], v[150:153], v[198:201], v[94:97]
	v_mfma_f32_16x16x32_bf16 v[78:81], v[150:153], v[206:209], v[78:81]
	v_mfma_f32_16x16x32_bf16 v[78:81], v[154:157], v[210:213], v[78:81]
	v_mfma_f32_16x16x32_bf16 v[82:85], v[146:149], v[210:213], v[82:85]
	v_mfma_f32_16x16x32_bf16 v[82:85], v[142:145], v[206:209], v[82:85]
	s_setprio 0
	s_setprio 1
	v_mfma_f32_16x16x32_bf16 v[122:125], v[158:161], v[182:185], v[122:125]
	v_mfma_f32_16x16x32_bf16 v[122:125], v[162:165], v[186:189], v[122:125]
	v_mfma_f32_16x16x32_bf16 v[118:121], v[170:173], v[186:189], v[118:121]
	v_mfma_f32_16x16x32_bf16 v[118:121], v[166:169], v[182:185], v[118:121]
	v_mfma_f32_16x16x32_bf16 v[102:105], v[166:169], v[190:193], v[102:105]
	v_mfma_f32_16x16x32_bf16 v[102:105], v[170:173], v[194:197], v[102:105]
	v_mfma_f32_16x16x32_bf16 v[106:109], v[162:165], v[194:197], v[106:109]
	v_mfma_f32_16x16x32_bf16 v[106:109], v[158:161], v[190:193], v[106:109]
	v_mfma_f32_16x16x32_bf16 v[90:93], v[158:161], v[198:201], v[90:93]
	v_mfma_f32_16x16x32_bf16 v[90:93], v[162:165], v[202:205], v[90:93]
	v_mfma_f32_16x16x32_bf16 v[86:89], v[170:173], v[202:205], v[86:89]
	v_mfma_f32_16x16x32_bf16 v[86:89], v[166:169], v[198:201], v[86:89]
	v_mfma_f32_16x16x32_bf16 v[70:73], v[166:169], v[206:209], v[70:73]
	v_mfma_f32_16x16x32_bf16 v[70:73], v[170:173], v[210:213], v[70:73]
	v_mfma_f32_16x16x32_bf16 v[74:77], v[162:165], v[210:213], v[74:77]
	v_mfma_f32_16x16x32_bf16 v[74:77], v[158:161], v[206:209], v[74:77]
	s_setprio 0
	s_barrier
	s_add_i32 s24, s48, s30
	v_lshl_add_u64 v[174:175], v[174:175], 0, s[92:93]
	s_mov_b32 m0, s24
	ds_read_b128 v[182:185], v251 offset:49152
	ds_read_b128 v[186:189], v251 offset:50176
	ds_read_b128 v[190:193], v251 offset:51200
	ds_read_b128 v[194:197], v251 offset:52224
	ds_read_b128 v[198:201], v251 offset:53248
	ds_read_b128 v[202:205], v251 offset:54272
	ds_read_b128 v[206:209], v251 offset:55296
	ds_read_b128 v[210:213], v251 offset:56320
	global_load_lds_dwordx4 v[174:175], off
	v_lshl_add_u64 v[174:175], v[214:215], 0, s[92:93]
	s_add_i32 m0, s24, 0x2000
	s_add_i32 s24, s49, s30
	global_load_lds_dwordx4 v[174:175], off
	v_lshl_add_u64 v[174:175], v[216:217], 0, s[92:93]
	s_mov_b32 m0, s24
	s_nop 0
	global_load_lds_dwordx4 v[174:175], off
	v_lshl_add_u64 v[174:175], v[218:219], 0, s[92:93]
	s_add_i32 m0, s24, 0x2000
	s_nop 0
	global_load_lds_dwordx4 v[174:175], off
	v_lshl_add_u64 v[174:175], v[220:221], 0, s[92:93]
	s_mov_b32 m0, s37
	s_nop 0
	global_load_lds_dwordx4 v[174:175], off
	v_lshl_add_u64 v[174:175], v[222:223], 0, s[92:93]
	s_mov_b32 m0, s38
	s_nop 0
	global_load_lds_dwordx4 v[174:175], off
	s_waitcnt vmcnt(8)
	s_waitcnt lgkmcnt(0)
	s_barrier
	s_setprio 1
	s_waitcnt lgkmcnt(0)
	v_mfma_f32_16x16x32_bf16 v[66:69], v[142:145], v[182:185], v[66:69]
	v_mfma_f32_16x16x32_bf16 v[66:69], v[146:149], v[186:189], v[66:69]
	v_mfma_f32_16x16x32_bf16 v[62:65], v[154:157], v[186:189], v[62:65]
	v_mfma_f32_16x16x32_bf16 v[62:65], v[150:153], v[182:185], v[62:65]
	v_mfma_f32_16x16x32_bf16 v[46:49], v[150:153], v[190:193], v[46:49]
	v_mfma_f32_16x16x32_bf16 v[46:49], v[154:157], v[194:197], v[46:49]
	v_mfma_f32_16x16x32_bf16 v[50:53], v[146:149], v[194:197], v[50:53]
	v_mfma_f32_16x16x32_bf16 v[50:53], v[142:145], v[190:193], v[50:53]
	v_mfma_f32_16x16x32_bf16 v[34:37], v[142:145], v[198:201], v[34:37]
	v_mfma_f32_16x16x32_bf16 v[34:37], v[146:149], v[202:205], v[34:37]
	v_mfma_f32_16x16x32_bf16 v[30:33], v[154:157], v[202:205], v[30:33]
	v_mfma_f32_16x16x32_bf16 v[30:33], v[150:153], v[198:201], v[30:33]
	v_mfma_f32_16x16x32_bf16 v[10:13], v[150:153], v[206:209], v[10:13]
	v_mfma_f32_16x16x32_bf16 v[10:13], v[154:157], v[210:213], v[10:13]
	v_mfma_f32_16x16x32_bf16 v[18:21], v[146:149], v[210:213], v[18:21]
	v_mfma_f32_16x16x32_bf16 v[18:21], v[142:145], v[206:209], v[18:21]
	s_setprio 0
	s_setprio 1
	v_mfma_f32_16x16x32_bf16 v[58:61], v[158:161], v[182:185], v[58:61]
	v_mfma_f32_16x16x32_bf16 v[58:61], v[162:165], v[186:189], v[58:61]
	v_mfma_f32_16x16x32_bf16 v[54:57], v[170:173], v[186:189], v[54:57]
	v_mfma_f32_16x16x32_bf16 v[54:57], v[166:169], v[182:185], v[54:57]
	v_mfma_f32_16x16x32_bf16 v[38:41], v[166:169], v[190:193], v[38:41]
	v_mfma_f32_16x16x32_bf16 v[38:41], v[170:173], v[194:197], v[38:41]
	v_mfma_f32_16x16x32_bf16 v[42:45], v[162:165], v[194:197], v[42:45]
	v_mfma_f32_16x16x32_bf16 v[42:45], v[158:161], v[190:193], v[42:45]
	v_mfma_f32_16x16x32_bf16 v[26:29], v[158:161], v[198:201], v[26:29]
	v_mfma_f32_16x16x32_bf16 v[26:29], v[162:165], v[202:205], v[26:29]
	v_mfma_f32_16x16x32_bf16 v[22:25], v[170:173], v[202:205], v[22:25]
	v_mfma_f32_16x16x32_bf16 v[22:25], v[166:169], v[198:201], v[22:25]
	v_mfma_f32_16x16x32_bf16 v[2:5], v[166:169], v[206:209], v[2:5]
	v_mfma_f32_16x16x32_bf16 v[2:5], v[170:173], v[210:213], v[2:5]
	v_mfma_f32_16x16x32_bf16 v[6:9], v[162:165], v[210:213], v[6:9]
	v_mfma_f32_16x16x32_bf16 v[6:9], v[158:161], v[206:209], v[6:9]
	s_setprio 0
	s_barrier
	s_add_u32 s22, s22, 0x100
	s_addc_u32 s23, s23, 0
	s_add_u32 s45, s45, 0x100
	s_addc_u32 s46, s46, 0
	s_cmp_ge_u32 s47, s39
	s_mov_b32 s24, s47
	s_cbranch_scc0 .LBB0_637
	s_and_b64 vcc, exec, s[18:19]
	s_cbranch_vccz .LBB0_640
	s_barrier

.Lg3_join_w1:
	s_waitcnt lgkmcnt(0)
	s_barrier
	s_setprio 1
	s_waitcnt lgkmcnt(0)
	v_mfma_f32_16x16x32_bf16 v[130:133], v[134:137], v[194:197], v[130:133]
	v_mfma_f32_16x16x32_bf16 v[130:133], v[148:151], v[198:201], v[130:133]
	v_mfma_f32_16x16x32_bf16 v[122:125], v[156:159], v[198:201], v[122:125]
	v_mfma_f32_16x16x32_bf16 v[122:125], v[152:155], v[194:197], v[122:125]
	v_mfma_f32_16x16x32_bf16 v[106:109], v[152:155], v[202:205], v[106:109]
	v_mfma_f32_16x16x32_bf16 v[106:109], v[156:159], v[206:209], v[106:109]
	v_mfma_f32_16x16x32_bf16 v[114:117], v[148:151], v[206:209], v[114:117]
	v_mfma_f32_16x16x32_bf16 v[114:117], v[134:137], v[202:205], v[114:117]
	v_mfma_f32_16x16x32_bf16 v[98:101], v[134:137], v[210:213], v[98:101]
	v_mfma_f32_16x16x32_bf16 v[98:101], v[148:151], v[214:217], v[98:101]
	v_mfma_f32_16x16x32_bf16 v[90:93], v[156:159], v[214:217], v[90:93]
	v_mfma_f32_16x16x32_bf16 v[90:93], v[152:155], v[210:213], v[90:93]
	v_mfma_f32_16x16x32_bf16 v[74:77], v[152:155], v[218:221], v[74:77]
	v_mfma_f32_16x16x32_bf16 v[74:77], v[156:159], v[222:225], v[74:77]
	v_mfma_f32_16x16x32_bf16 v[82:85], v[148:151], v[222:225], v[82:85]
	v_mfma_f32_16x16x32_bf16 v[82:85], v[134:137], v[218:221], v[82:85]
	s_setprio 0
	s_setprio 1
	v_mfma_f32_16x16x32_bf16 v[126:129], v[160:163], v[194:197], v[126:129]
	v_mfma_f32_16x16x32_bf16 v[126:129], v[182:185], v[198:201], v[126:129]
	v_mfma_f32_16x16x32_bf16 v[118:121], v[190:193], v[198:201], v[118:121]
	v_mfma_f32_16x16x32_bf16 v[118:121], v[186:189], v[194:197], v[118:121]
	v_mfma_f32_16x16x32_bf16 v[102:105], v[186:189], v[202:205], v[102:105]
	v_mfma_f32_16x16x32_bf16 v[102:105], v[190:193], v[206:209], v[102:105]
	v_mfma_f32_16x16x32_bf16 v[110:113], v[182:185], v[206:209], v[110:113]
	v_mfma_f32_16x16x32_bf16 v[110:113], v[160:163], v[202:205], v[110:113]
	v_mfma_f32_16x16x32_bf16 v[94:97], v[160:163], v[210:213], v[94:97]
	v_mfma_f32_16x16x32_bf16 v[94:97], v[182:185], v[214:217], v[94:97]
	v_mfma_f32_16x16x32_bf16 v[86:89], v[190:193], v[214:217], v[86:89]
	v_mfma_f32_16x16x32_bf16 v[86:89], v[186:189], v[210:213], v[86:89]
	v_mfma_f32_16x16x32_bf16 v[70:73], v[186:189], v[218:221], v[70:73]
	v_mfma_f32_16x16x32_bf16 v[70:73], v[190:193], v[222:225], v[70:73]
	v_mfma_f32_16x16x32_bf16 v[78:81], v[182:185], v[222:225], v[78:81]
	v_mfma_f32_16x16x32_bf16 v[78:81], v[160:163], v[218:221], v[78:81]
	s_setprio 0
	s_barrier
	s_add_i32 s41, s41, s13
	v_lshl_add_u64 v[226:227], s[20:21], 0, v[0:1]
	s_mov_b32 m0, s41
	ds_read_b128 v[194:197], v175 offset:16384
	ds_read_b128 v[198:201], v175 offset:17408
	ds_read_b128 v[202:205], v175 offset:18432
	ds_read_b128 v[206:209], v175 offset:19456
	ds_read_b128 v[210:213], v175 offset:20480
	ds_read_b128 v[214:217], v175 offset:21504
	ds_read_b128 v[218:221], v175 offset:22528
	ds_read_b128 v[222:225], v175 offset:23552
	global_load_lds_dwordx4 v[226:227], off
	s_add_i32 m0, s41, 0x2000
	s_add_u32 s42, s20, 0x40000
	v_lshl_add_u64 v[228:229], s[20:21], 0, v[14:15]
	s_addc_u32 s43, s21, 0
	s_add_i32 s41, s44, s13
	global_load_lds_dwordx4 v[228:229], off
	v_lshl_add_u64 v[230:231], s[42:43], 0, v[0:1]
	s_mov_b32 m0, s41
	v_lshl_add_u64 v[232:233], s[22:23], 0, v[138:139]
	global_load_lds_dwordx4 v[230:231], off
	v_lshl_add_u64 v[230:231], s[42:43], 0, v[14:15]
	s_add_i32 m0, s41, 0x2000
	s_nop 0
	global_load_lds_dwordx4 v[230:231], off
	v_lshl_add_u64 v[230:231], s[22:23], 0, v[140:141]
	s_mov_b32 m0, s26
	s_nop 0
	global_load_lds_dwordx4 v[230:231], off
	s_mov_b32 m0, s27
	s_nop 0
	global_load_lds_dwordx4 v[232:233], off
	s_cmp_eq_i32 s40, -2
	s_cselect_b32 s98, s2, 0
	s_cmp_lg_u32 s98, 0
	s_cbranch_scc1 .Lg3_relax_w2
	s_waitcnt vmcnt(8)
	s_branch .Lg3_join_w2

.Lg3_join_w2:
	s_waitcnt lgkmcnt(0)
	s_barrier
	s_setprio 1
	s_waitcnt lgkmcnt(0)
	v_mfma_f32_16x16x32_bf16 v[66:69], v[134:137], v[194:197], v[66:69]
	v_mfma_f32_16x16x32_bf16 v[66:69], v[148:151], v[198:201], v[66:69]
	v_mfma_f32_16x16x32_bf16 v[58:61], v[156:159], v[198:201], v[58:61]
	v_mfma_f32_16x16x32_bf16 v[58:61], v[152:155], v[194:197], v[58:61]
	v_mfma_f32_16x16x32_bf16 v[42:45], v[152:155], v[202:205], v[42:45]
	v_mfma_f32_16x16x32_bf16 v[42:45], v[156:159], v[206:209], v[42:45]
	v_mfma_f32_16x16x32_bf16 v[50:53], v[148:151], v[206:209], v[50:53]
	v_mfma_f32_16x16x32_bf16 v[50:53], v[134:137], v[202:205], v[50:53]
	v_mfma_f32_16x16x32_bf16 v[34:37], v[134:137], v[210:213], v[34:37]
	v_mfma_f32_16x16x32_bf16 v[34:37], v[148:151], v[214:217], v[34:37]
	v_mfma_f32_16x16x32_bf16 v[26:29], v[156:159], v[214:217], v[26:29]
	v_mfma_f32_16x16x32_bf16 v[26:29], v[152:155], v[210:213], v[26:29]
	v_mfma_f32_16x16x32_bf16 v[6:9], v[152:155], v[218:221], v[6:9]
	v_mfma_f32_16x16x32_bf16 v[6:9], v[156:159], v[222:225], v[6:9]
	v_mfma_f32_16x16x32_bf16 v[18:21], v[148:151], v[222:225], v[18:21]
	v_mfma_f32_16x16x32_bf16 v[18:21], v[134:137], v[218:221], v[18:21]
	s_setprio 0
	s_setprio 1
	v_mfma_f32_16x16x32_bf16 v[62:65], v[160:163], v[194:197], v[62:65]
	v_mfma_f32_16x16x32_bf16 v[62:65], v[182:185], v[198:201], v[62:65]
	v_mfma_f32_16x16x32_bf16 v[54:57], v[190:193], v[198:201], v[54:57]
	v_mfma_f32_16x16x32_bf16 v[54:57], v[186:189], v[194:197], v[54:57]
	v_mfma_f32_16x16x32_bf16 v[38:41], v[186:189], v[202:205], v[38:41]
	v_mfma_f32_16x16x32_bf16 v[38:41], v[190:193], v[206:209], v[38:41]
	v_mfma_f32_16x16x32_bf16 v[46:49], v[182:185], v[206:209], v[46:49]
	v_mfma_f32_16x16x32_bf16 v[46:49], v[160:163], v[202:205], v[46:49]
	v_mfma_f32_16x16x32_bf16 v[30:33], v[160:163], v[210:213], v[30:33]
	v_mfma_f32_16x16x32_bf16 v[30:33], v[182:185], v[214:217], v[30:33]
	v_mfma_f32_16x16x32_bf16 v[22:25], v[190:193], v[214:217], v[22:25]
	v_mfma_f32_16x16x32_bf16 v[22:25], v[186:189], v[210:213], v[22:25]
	v_mfma_f32_16x16x32_bf16 v[2:5], v[186:189], v[218:221], v[2:5]
	v_mfma_f32_16x16x32_bf16 v[2:5], v[190:193], v[222:225], v[2:5]
	v_mfma_f32_16x16x32_bf16 v[10:13], v[182:185], v[222:225], v[10:13]
	v_mfma_f32_16x16x32_bf16 v[10:13], v[160:163], v[218:221], v[10:13]
	s_setprio 0
	s_barrier
	s_add_i32 s41, 0, 0x18000
	s_add_i32 s42, 0, 0x1c000
	v_add_u32_e32 v156, s41, v171
	v_add_u32_e32 v164, s42, v171
	ds_read_b128 v[134:137], v156
	ds_read_b128 v[148:151], v156 offset:1024
	ds_read_b128 v[152:155], v156 offset:2048
	ds_read_b128 v[156:159], v156 offset:3072
	ds_read_b128 v[160:163], v164
	ds_read_b128 v[182:185], v164 offset:1024
	ds_read_b128 v[186:189], v164 offset:2048
	ds_read_b128 v[190:193], v164 offset:3072
	s_add_u32 s22, s22, 0x40000
	s_addc_u32 s23, s23, 0
	s_mov_b32 m0, s28
	v_lshl_add_u64 v[234:235], s[22:23], 0, v[140:141]
	ds_read_b128 v[194:197], v175 offset:32768
	ds_read_b128 v[198:201], v175 offset:33792
	ds_read_b128 v[202:205], v175 offset:34816
	ds_read_b128 v[206:209], v175 offset:35840
	ds_read_b128 v[210:213], v175 offset:36864
	ds_read_b128 v[214:217], v175 offset:37888
	ds_read_b128 v[218:221], v175 offset:38912
	ds_read_b128 v[222:225], v175 offset:39936
	global_load_lds_dwordx4 v[234:235], off
	v_lshl_add_u64 v[234:235], s[22:23], 0, v[138:139]
	s_mov_b32 m0, s29
	s_nop 0
	global_load_lds_dwordx4 v[234:235], off
	s_waitcnt vmcnt(8)
	s_waitcnt lgkmcnt(0)
	s_barrier
	s_setprio 1
	s_waitcnt lgkmcnt(0)
	v_mfma_f32_16x16x32_bf16 v[130:133], v[134:137], v[194:197], v[130:133]
	v_mfma_f32_16x16x32_bf16 v[130:133], v[148:151], v[198:201], v[130:133]
	v_mfma_f32_16x16x32_bf16 v[122:125], v[156:159], v[198:201], v[122:125]
	v_mfma_f32_16x16x32_bf16 v[122:125], v[152:155], v[194:197], v[122:125]
	v_mfma_f32_16x16x32_bf16 v[106:109], v[152:155], v[202:205], v[106:109]
	v_mfma_f32_16x16x32_bf16 v[106:109], v[156:159], v[206:209], v[106:109]
	v_mfma_f32_16x16x32_bf16 v[114:117], v[148:151], v[206:209], v[114:117]
	v_mfma_f32_16x16x32_bf16 v[114:117], v[134:137], v[202:205], v[114:117]
	v_mfma_f32_16x16x32_bf16 v[98:101], v[134:137], v[210:213], v[98:101]
	v_mfma_f32_16x16x32_bf16 v[98:101], v[148:151], v[214:217], v[98:101]
	v_mfma_f32_16x16x32_bf16 v[90:93], v[156:159], v[214:217], v[90:93]
	v_mfma_f32_16x16x32_bf16 v[90:93], v[152:155], v[210:213], v[90:93]
	v_mfma_f32_16x16x32_bf16 v[74:77], v[152:155], v[218:221], v[74:77]
	v_mfma_f32_16x16x32_bf16 v[74:77], v[156:159], v[222:225], v[74:77]
	v_mfma_f32_16x16x32_bf16 v[82:85], v[148:151], v[222:225], v[82:85]
	v_mfma_f32_16x16x32_bf16 v[82:85], v[134:137], v[218:221], v[82:85]
	s_setprio 0
	s_setprio 1
	v_mfma_f32_16x16x32_bf16 v[126:129], v[160:163], v[194:197], v[126:129]
	v_mfma_f32_16x16x32_bf16 v[126:129], v[182:185], v[198:201], v[126:129]
	v_mfma_f32_16x16x32_bf16 v[118:121], v[190:193], v[198:201], v[118:121]
	v_mfma_f32_16x16x32_bf16 v[118:121], v[186:189], v[194:197], v[118:121]
	v_mfma_f32_16x16x32_bf16 v[102:105], v[186:189], v[202:205], v[102:105]
	v_mfma_f32_16x16x32_bf16 v[102:105], v[190:193], v[206:209], v[102:105]
	v_mfma_f32_16x16x32_bf16 v[110:113], v[182:185], v[206:209], v[110:113]
	v_mfma_f32_16x16x32_bf16 v[110:113], v[160:163], v[202:205], v[110:113]
	v_mfma_f32_16x16x32_bf16 v[94:97], v[160:163], v[210:213], v[94:97]
	v_mfma_f32_16x16x32_bf16 v[94:97], v[182:185], v[214:217], v[94:97]
	v_mfma_f32_16x16x32_bf16 v[86:89], v[190:193], v[214:217], v[86:89]
	v_mfma_f32_16x16x32_bf16 v[86:89], v[186:189], v[210:213], v[86:89]
	v_mfma_f32_16x16x32_bf16 v[70:73], v[186:189], v[218:221], v[70:73]
	v_mfma_f32_16x16x32_bf16 v[70:73], v[190:193], v[222:225], v[70:73]
	v_mfma_f32_16x16x32_bf16 v[78:81], v[182:185], v[222:225], v[78:81]
	v_mfma_f32_16x16x32_bf16 v[78:81], v[160:163], v[218:221], v[78:81]
	s_setprio 0
	s_barrier
	s_add_i32 s22, s41, s13
	v_lshl_add_u64 v[226:227], v[226:227], 0, s[92:93]
	s_mov_b32 m0, s22
	ds_read_b128 v[194:197], v175 offset:49152
	ds_read_b128 v[198:201], v175 offset:50176
	ds_read_b128 v[202:205], v175 offset:51200
	ds_read_b128 v[206:209], v175 offset:52224
	ds_read_b128 v[210:213], v175 offset:53248
	ds_read_b128 v[214:217], v175 offset:54272
	ds_read_b128 v[218:221], v175 offset:55296
	ds_read_b128 v[222:225], v175 offset:56320
	global_load_lds_dwordx4 v[226:227], off
	s_add_i32 m0, s22, 0x2000
	s_add_u32 s20, s20, 0x40080
	v_lshl_add_u64 v[226:227], v[228:229], 0, s[92:93]
	s_addc_u32 s21, s21, 0
	s_add_i32 s22, s42, s13
	global_load_lds_dwordx4 v[226:227], off
	v_lshl_add_u64 v[226:227], s[20:21], 0, v[0:1]
	s_mov_b32 m0, s22
	s_nop 0
	global_load_lds_dwordx4 v[226:227], off
	v_lshl_add_u64 v[226:227], s[20:21], 0, v[14:15]
	s_add_i32 m0, s22, 0x2000
	s_nop 0
	global_load_lds_dwordx4 v[226:227], off
	v_lshl_add_u64 v[226:227], v[230:231], 0, s[92:93]
	s_mov_b32 m0, s30
	s_nop 0
	global_load_lds_dwordx4 v[226:227], off
	v_lshl_add_u64 v[226:227], v[232:233], 0, s[92:93]
	s_mov_b32 m0, s31
	s_nop 0
	global_load_lds_dwordx4 v[226:227], off
	s_waitcnt vmcnt(8)
	s_waitcnt lgkmcnt(0)
	s_barrier
	s_setprio 1
	s_waitcnt lgkmcnt(0)
	v_mfma_f32_16x16x32_bf16 v[66:69], v[134:137], v[194:197], v[66:69]
	v_mfma_f32_16x16x32_bf16 v[66:69], v[148:151], v[198:201], v[66:69]
	v_mfma_f32_16x16x32_bf16 v[58:61], v[156:159], v[198:201], v[58:61]
	v_mfma_f32_16x16x32_bf16 v[58:61], v[152:155], v[194:197], v[58:61]
	v_mfma_f32_16x16x32_bf16 v[42:45], v[152:155], v[202:205], v[42:45]
	v_mfma_f32_16x16x32_bf16 v[42:45], v[156:159], v[206:209], v[42:45]
	v_mfma_f32_16x16x32_bf16 v[50:53], v[148:151], v[206:209], v[50:53]
	v_mfma_f32_16x16x32_bf16 v[50:53], v[134:137], v[202:205], v[50:53]
	v_mfma_f32_16x16x32_bf16 v[34:37], v[134:137], v[210:213], v[34:37]
	v_mfma_f32_16x16x32_bf16 v[34:37], v[148:151], v[214:217], v[34:37]
	v_mfma_f32_16x16x32_bf16 v[26:29], v[156:159], v[214:217], v[26:29]
	v_mfma_f32_16x16x32_bf16 v[26:29], v[152:155], v[210:213], v[26:29]
	v_mfma_f32_16x16x32_bf16 v[6:9], v[152:155], v[218:221], v[6:9]
	v_mfma_f32_16x16x32_bf16 v[6:9], v[156:159], v[222:225], v[6:9]
	v_mfma_f32_16x16x32_bf16 v[18:21], v[148:151], v[222:225], v[18:21]
	v_mfma_f32_16x16x32_bf16 v[18:21], v[134:137], v[218:221], v[18:21]
	s_setprio 0
	s_setprio 1
	v_mfma_f32_16x16x32_bf16 v[62:65], v[160:163], v[194:197], v[62:65]
	v_mfma_f32_16x16x32_bf16 v[62:65], v[182:185], v[198:201], v[62:65]
	v_mfma_f32_16x16x32_bf16 v[54:57], v[190:193], v[198:201], v[54:57]
	v_mfma_f32_16x16x32_bf16 v[54:57], v[186:189], v[194:197], v[54:57]
	v_mfma_f32_16x16x32_bf16 v[38:41], v[186:189], v[202:205], v[38:41]
	v_mfma_f32_16x16x32_bf16 v[38:41], v[190:193], v[206:209], v[38:41]
	v_mfma_f32_16x16x32_bf16 v[46:49], v[182:185], v[206:209], v[46:49]
	v_mfma_f32_16x16x32_bf16 v[46:49], v[160:163], v[202:205], v[46:49]
	v_mfma_f32_16x16x32_bf16 v[30:33], v[160:163], v[210:213], v[30:33]
	v_mfma_f32_16x16x32_bf16 v[30:33], v[182:185], v[214:217], v[30:33]
	v_mfma_f32_16x16x32_bf16 v[22:25], v[190:193], v[214:217], v[22:25]
	v_mfma_f32_16x16x32_bf16 v[22:25], v[186:189], v[210:213], v[22:25]
	v_mfma_f32_16x16x32_bf16 v[2:5], v[186:189], v[218:221], v[2:5]
	v_mfma_f32_16x16x32_bf16 v[2:5], v[190:193], v[222:225], v[2:5]
	v_mfma_f32_16x16x32_bf16 v[10:13], v[182:185], v[222:225], v[10:13]
	v_mfma_f32_16x16x32_bf16 v[10:13], v[160:163], v[218:221], v[10:13]
	s_setprio 0
	s_barrier
	s_add_i32 s40, s40, 2
	s_add_u32 s4, s4, 0x100
	s_addc_u32 s5, s5, 0
	s_add_u32 s38, s38, 0x100
	s_addc_u32 s39, s39, 0
	s_cmp_gt_u32 s40, 13
	s_cbranch_scc0 .LBB0_893
	s_and_b64 vcc, exec, s[8:9]
	s_cbranch_vccz .LBB0_896
	s_barrier
